# F with 4 bytes of entry padding (code placement check)
# speedup vs baseline: 1.0042x; 1.0042x over previous
; #define LAS __attribute__((address_space(3)))
; __global__ void __launch_bounds__(NTHR, 2) fwd_megakernel(Args args) {
;     extern __shared__ __attribute__((aligned(16))) unsigned char lds_raw[];
;     LAS unsigned char* lds = (LAS unsigned char*)lds_raw;
;     cg::grid_group grid = cg::this_grid();
;     if (gridDim.x == 0x7fffffffu) grid.sync();
;     { volatile LAS unsigned* mz = (volatile LAS unsigned*)(lds + LDS_BYTES - 64); if (threadIdx.x < 16) mz[threadIdx.x] = 0u; }
_Z14fwd_megakernel4Args:
	s_nop 0
	s_load_dwordx2 s[6:7], s[0:1], 0x90
	s_load_dwordx16 s[68:83], s[0:1], 0x0
	s_load_dwordx16 s[52:67], s[0:1], 0x40
	s_add_u32 s8, s0, 0x90
	s_addc_u32 s9, s1, 0
	s_waitcnt lgkmcnt(0)
	s_cmp_eq_u32 s6, 0x7fffffff
	s_cbranch_scc1 .LBB0_2
	v_and_b32_e32 v216, 0x3ff, v0
	s_load_dword s3, s[0:1], 0x98
	s_cbranch_execz .LBB0_3
	s_branch .LBB0_14
